# diff loop: persistent per-lane K/V load pointers (no per-tile carry-chain address math)
# speedup vs baseline: 1.0776x; 1.0082x over previous
; #define GAS __attribute__((address_space(1)))
; template <int KW, int DV, bool BIAS> ...
;     ...
;     const bf16* ksrc = Kg + (size_t)krow * ZLD + kch * 8;
;     const bf16* vsrc = Vtg + (size_t)vrow * (size_t)N + vch * 8;
;     u32x4 kreg[KP], vreg[VP];
; #pragma unroll
;     for (int i = 0; i < KP; ++i) kreg[i] = *(const GAS u32x4*)(ksrc + (size_t)((NTHR / KPR) * i) * ZLD);
; #pragma unroll
;     for (int i = 0; i < VP; ++i) vreg[i] = *(const GAS u32x4*)(vsrc + (size_t)(64 * i) * (size_t)N);
.LBB0_268:
	v_lshl_add_u64 v[158:159], v[154:155], 0, s[72:73]
	v_lshl_add_u64 v[156:157], v[152:153], 0, s[72:73]
	s_mov_b32 s4, 0x2f800000
	s_mov_b32 s5, 0
	v_lshl_add_u64 v[158:159], v[158:159], 0, s[4:5]
	v_lshl_add_u64 v[156:157], v[156:157], 0, s[4:5]
	s_mov_b32 s5, -1
	s_mov_b32 s4, 0xfff94000
	v_lshl_add_u64 v[208:209], v[150:151], 0, s[4:5]
	s_mov_b32 s4, 0xfffb8000
	v_lshl_add_u64 v[210:211], v[150:151], 0, s[4:5]
	s_mov_b32 s4, 0xfffdc000
	v_lshl_add_u64 v[212:213], v[150:151], 0, s[4:5]
	s_waitcnt vmcnt(3)
	ds_write_b128 v180, v[98:101]
	s_waitcnt vmcnt(2)
	ds_write_b128 v180, v[102:105] offset:8192
	s_waitcnt vmcnt(0)
	ds_write2st64_b64 v178, v[106:107], v[110:111] offset0:32 offset1:48
	ds_write2st64_b64 v179, v[108:109], v[112:113] offset0:32 offset1:48
	s_add_i32 s4, s64, -1
	s_cmp_ge_u32 s4, s18
	s_cbranch_scc1 .Ldg_nold1
	global_load_dwordx4 v[98:101], v[208:209], off
	global_load_dwordx4 v[102:105], v[210:211], off
	global_load_dwordx4 v[106:109], v[158:159], off offset:384
	global_load_dwordx4 v[110:113], v[156:157], off offset:384

.Ldg_join1_3:
	s_waitcnt lgkmcnt(3)
	v_mfma_f32_32x32x16_bf16 v[0:15], v[160:163], v[126:129], v[0:15]
	ds_read_b128 v[130:133], v195 offset:24576
	ds_read_b128 v[134:137], v195 offset:28672
	v_add_f32_e32 v168, v236, v237
	v_add_f32_e32 v169, v238, v239
	v_add_f32_e32 v170, v240, v241
	v_add_f32_e32 v171, v242, v243
	v_add_f32_e32 v172, v244, v245
	v_add_f32_e32 v173, v246, v247
	s_waitcnt lgkmcnt(4)
	v_mfma_f32_32x32x16_bf16 v[16:31], v[160:163], v[114:117], v[16:31]
	ds_read_b128 v[138:141], v196 offset:24576
	ds_read_b128 v[142:145], v196 offset:28672
	v_add_f32_e32 v174, v248, v249
	v_add_f32_e32 v175, v250, v251
	v_add_f32_e32 v168, v168, v169
	v_add_f32_e32 v170, v170, v171
	v_add_f32_e32 v172, v172, v173
	s_waitcnt lgkmcnt(5)
	v_mfma_f32_32x32x16_bf16 v[0:15], v[164:167], v[122:125], v[0:15]
	v_add_f32_e32 v174, v174, v175
	v_add_f32_e32 v168, v168, v170
	v_add_f32_e32 v172, v172, v174
	v_add_f32_e32 v168, v168, v172
	v_add_f32_e32 v184, v184, v168
	s_waitcnt lgkmcnt(4)
	v_mfma_f32_32x32x16_bf16 v[16:31], v[164:167], v[118:121], v[16:31]
	s_waitcnt lgkmcnt(3)
	v_mfma_f32_32x32x16_bf16 v[32:47], v[160:163], v[130:133], v[32:47]
	s_waitcnt lgkmcnt(2)
	v_mfma_f32_32x32x16_bf16 v[48:63], v[160:163], v[134:137], v[48:63]
	s_waitcnt lgkmcnt(1)
	v_mfma_f32_32x32x16_bf16 v[32:47], v[164:167], v[138:141], v[32:47]
	s_waitcnt lgkmcnt(0)
	v_mfma_f32_32x32x16_bf16 v[48:63], v[164:167], v[142:145], v[48:63]
	s_waitcnt vmcnt(3)
	ds_write_b128 v180, v[98:101] offset:32768
	s_waitcnt vmcnt(2)
	ds_write_b128 v180, v[102:105] offset:40960
	s_waitcnt vmcnt(0)
	ds_write2st64_b64 v178, v[106:107], v[110:111] offset0:96 offset1:112
	ds_write2st64_b64 v179, v[108:109], v[112:113] offset0:96 offset1:112
	s_cmp_ge_u32 s64, s18
	s_cbranch_scc1 .Ldg_nold4
	global_load_dwordx4 v[98:101], v[212:213], off
	global_load_dwordx4 v[102:105], v[150:151], off
	global_load_dwordx4 v[106:109], v[158:159], off offset:512
	global_load_dwordx4 v[110:113], v[156:157], off offset:512

.Ldg_join1_6:
	s_waitcnt lgkmcnt(3)
	v_mfma_f32_32x32x16_bf16 v[0:15], v[160:163], v[126:129], v[0:15]
	ds_read_b128 v[130:133], v195 offset:57344
	ds_read_b128 v[134:137], v195 offset:61440
	v_add_f32_e32 v168, v236, v237
	v_add_f32_e32 v169, v238, v239
	v_add_f32_e32 v170, v240, v241
	v_add_f32_e32 v171, v242, v243
	v_add_f32_e32 v172, v244, v245
	v_add_f32_e32 v173, v246, v247
	s_waitcnt lgkmcnt(4)
	v_mfma_f32_32x32x16_bf16 v[16:31], v[160:163], v[114:117], v[16:31]
	ds_read_b128 v[138:141], v196 offset:57344
	ds_read_b128 v[142:145], v196 offset:61440
	v_add_f32_e32 v174, v248, v249
	v_add_f32_e32 v175, v250, v251
	v_add_f32_e32 v168, v168, v169
	v_add_f32_e32 v170, v170, v171
	v_add_f32_e32 v172, v172, v173
	s_waitcnt lgkmcnt(5)
	v_mfma_f32_32x32x16_bf16 v[0:15], v[164:167], v[122:125], v[0:15]
	v_add_f32_e32 v174, v174, v175
	v_add_f32_e32 v168, v168, v170
	v_add_f32_e32 v172, v172, v174
	v_add_f32_e32 v168, v168, v172
	v_add_f32_e32 v184, v184, v168
	s_waitcnt lgkmcnt(4)
	v_mfma_f32_32x32x16_bf16 v[16:31], v[164:167], v[118:121], v[16:31]
	s_waitcnt lgkmcnt(3)
	v_mfma_f32_32x32x16_bf16 v[32:47], v[160:163], v[130:133], v[32:47]
	s_waitcnt lgkmcnt(2)
	v_mfma_f32_32x32x16_bf16 v[48:63], v[160:163], v[134:137], v[48:63]
	s_waitcnt lgkmcnt(1)
	v_mfma_f32_32x32x16_bf16 v[32:47], v[164:167], v[138:141], v[32:47]
	s_waitcnt lgkmcnt(0)
	v_mfma_f32_32x32x16_bf16 v[48:63], v[164:167], v[142:145], v[48:63]
	s_cmp_ge_u32 s64, s18
	s_cbranch_scc1 .Ldg_aexit
	s_waitcnt vmcnt(3)
	ds_write_b128 v180, v[98:101]
	s_waitcnt vmcnt(2)
	ds_write_b128 v180, v[102:105] offset:8192
	s_waitcnt vmcnt(0)
	ds_write2st64_b64 v178, v[106:107], v[110:111] offset0:32 offset1:48
	ds_write2st64_b64 v179, v[108:109], v[112:113] offset0:32 offset1:48
	v_lshl_add_u64 v[150:151], v[150:151], 0, s[94:95]
	v_lshl_add_u64 v[208:209], v[208:209], 0, s[94:95]
	v_lshl_add_u64 v[210:211], v[210:211], 0, s[94:95]
	v_lshl_add_u64 v[212:213], v[212:213], 0, s[94:95]
	v_lshl_add_u64 v[156:157], v[156:157], 0, s[84:85]
	v_lshl_add_u64 v[158:159], v[158:159], 0, s[84:85]
	s_add_i32 s64, s64, 2
	s_add_i32 s4, s64, -1
	s_cmp_ge_u32 s4, s18
	s_cbranch_scc1 .Ldg_nold7
	global_load_dwordx4 v[98:101], v[208:209], off
	global_load_dwordx4 v[102:105], v[210:211], off
	global_load_dwordx4 v[106:109], v[158:159], off offset:384
	global_load_dwordx4 v[110:113], v[156:157], off offset:384

.Ldg_back0_9:
	v_exp_f32_e32 v66, v66
	v_exp_f32_e32 v67, v67
	v_exp_f32_e32 v68, v68
	v_exp_f32_e32 v69, v69
	v_exp_f32_e32 v70, v70
	v_exp_f32_e32 v71, v71
	v_exp_f32_e32 v72, v72
	v_exp_f32_e32 v73, v73
	v_exp_f32_e32 v74, v74
	v_exp_f32_e32 v75, v75
	v_exp_f32_e32 v76, v76
	v_exp_f32_e32 v77, v77
	v_exp_f32_e32 v78, v78
	v_exp_f32_e32 v79, v79
	v_exp_f32_e32 v80, v80
	v_exp_f32_e32 v81, v81
	v_cvt_pk_bf16_f32 v200, v66, v67
	v_cvt_pk_bf16_f32 v201, v68, v69
	v_cvt_pk_bf16_f32 v202, v70, v71
	v_cvt_pk_bf16_f32 v203, v72, v73
	v_cvt_pk_bf16_f32 v204, v74, v75
	v_cvt_pk_bf16_f32 v205, v76, v77
	v_cvt_pk_bf16_f32 v206, v78, v79
	v_cvt_pk_bf16_f32 v207, v80, v81
	s_waitcnt vmcnt(3)
	ds_write_b128 v180, v[98:101] offset:32768
	s_waitcnt vmcnt(2)
	ds_write_b128 v180, v[102:105] offset:40960
	s_waitcnt vmcnt(0)
	ds_write2st64_b64 v178, v[106:107], v[110:111] offset0:96 offset1:112
	ds_write2st64_b64 v179, v[108:109], v[112:113] offset0:96 offset1:112
	s_cmp_ge_u32 s64, s18
	s_cbranch_scc1 .Ldg_nold10
	global_load_dwordx4 v[98:101], v[212:213], off
	global_load_dwordx4 v[102:105], v[150:151], off
	global_load_dwordx4 v[106:109], v[158:159], off offset:512
	global_load_dwordx4 v[110:113], v[156:157], off offset:512

.Ldg_back0_12:
	v_exp_f32_e32 v66, v66
	v_exp_f32_e32 v67, v67
	v_exp_f32_e32 v68, v68
	v_exp_f32_e32 v69, v69
	v_exp_f32_e32 v70, v70
	v_exp_f32_e32 v71, v71
	v_exp_f32_e32 v72, v72
	v_exp_f32_e32 v73, v73
	v_exp_f32_e32 v74, v74
	v_exp_f32_e32 v75, v75
	v_exp_f32_e32 v76, v76
	v_exp_f32_e32 v77, v77
	v_exp_f32_e32 v78, v78
	v_exp_f32_e32 v79, v79
	v_exp_f32_e32 v80, v80
	v_exp_f32_e32 v81, v81
	v_cvt_pk_bf16_f32 v200, v66, v67
	v_cvt_pk_bf16_f32 v201, v68, v69
	v_cvt_pk_bf16_f32 v202, v70, v71
	v_cvt_pk_bf16_f32 v203, v72, v73
	v_cvt_pk_bf16_f32 v204, v74, v75
	v_cvt_pk_bf16_f32 v205, v76, v77
	v_cvt_pk_bf16_f32 v206, v78, v79
	v_cvt_pk_bf16_f32 v207, v80, v81
	s_waitcnt vmcnt(3)
	ds_write_b128 v180, v[98:101]
	s_waitcnt vmcnt(2)
	ds_write_b128 v180, v[102:105] offset:8192
	s_waitcnt vmcnt(0)
	ds_write2st64_b64 v178, v[106:107], v[110:111] offset0:32 offset1:48
	ds_write2st64_b64 v179, v[108:109], v[112:113] offset0:32 offset1:48
	v_lshl_add_u64 v[150:151], v[150:151], 0, s[94:95]
	v_lshl_add_u64 v[208:209], v[208:209], 0, s[94:95]
	v_lshl_add_u64 v[210:211], v[210:211], 0, s[94:95]
	v_lshl_add_u64 v[212:213], v[212:213], 0, s[94:95]
	v_lshl_add_u64 v[156:157], v[156:157], 0, s[84:85]
	v_lshl_add_u64 v[158:159], v[158:159], 0, s[84:85]
	s_add_i32 s64, s64, 2
	s_add_i32 s4, s64, -1
	s_cmp_ge_u32 s4, s18
	s_cbranch_scc1 .Ldg_nold13
	global_load_dwordx4 v[98:101], v[208:209], off
	global_load_dwordx4 v[102:105], v[210:211], off
	global_load_dwordx4 v[106:109], v[158:159], off offset:384
	global_load_dwordx4 v[110:113], v[156:157], off offset:384
